# P6 residual epilogue restructured: x loads pipelined 4 row groups deep, stores after all loads issued; plus P5, P7 epilogue changes
# speedup vs baseline: 1.0140x; 1.0002x over previous
; DI unsigned pk2(float lo, float hi) { const f32x2 v = {lo, hi}; const bf16x2_t b = __builtin_convertvector(v, bf16x2_t); return __builtin_bit_cast(unsigned, b); }
;     DI void operator()(const Acc& acc, const Unit& u, int wr, int wc, int fr, int fq) const {
;     ...
;                 const int r = row0 + ai * 128 + m * 16; float ss = 0.f;
; #pragma unroll
;                 for (int bj = 0; bj < 2; ++bj) {
;                     const int c0 = u.pn * 256 + bj * 128 + wc * 32 + 8 * fq; const size_t off = (size_t)r * DM + c0;
;                     f32x4 b0, b1;
;                     if (MODE == 1) { b0 = *(const f32x4*)(base + off); b1 = *(const f32x4*)(base + off + 4); }
;                     else { const u32x4 w = *(const u32x4*)(baseb + off); b0 = (f32x4){bflo(w.x), bfhi(w.x), bflo(w.y), bfhi(w.y)}; b1 = (f32x4){bflo(w.z), bfhi(w.z), bflo(w.w), bfhi(w.w)}; }
;                     const f32x4 h0 = b0 + acc[ai][bj][m][0], h1 = b1 + acc[ai][bj][m][1];
;                     ss += (h0[0] * h0[0] + h0[1] * h0[1]) + (h0[2] * h0[2] + h0[3] * h0[3]) + (h1[0] * h1[0] + h1[1] * h1[1]) + (h1[2] * h1[2] + h1[3] * h1[3]);
;                     if (MODE == 1) { u32x4 w; w.x = pk2(h0[0], h0[1]); w.y = pk2(h0[2], h0[3]); w.z = pk2(h1[0], h1[1]); w.w = pk2(h1[2], h1[3]); *(u32x4*)(HB + off) = w; }
;                     else { u32x4 w; w.x = pk2(h0[0], h0[1]); w.y = pk2(h0[2], h0[3]); w.z = pk2(h1[0], h1[1]); w.w = pk2(h1[2], h1[3]); *(u32x4*)(HB + off) = w; }
;                 }
;                 ss += __shfl_xor(ss, 16); ss += __shfl_xor(ss, 32);
;                 if (fq == 0) SS[(size_t)r * 16 + u.pn * 4 + wc] = ss;
.LBB0_953:
	v_lshl_add_u32 v148, s48, 8, v1
	v_lshl_or_b32 v146, s16, 8, v151
	s_lshl_b32 s48, s16, 4
	s_lshl_b32 s16, s59, 2
	s_add_i32 s48, s48, s16
	v_lshlrev_b32_e32 v147, 2, v146
	v_lshl_add_u32 v149, v148, 12, v147
	v_lshlrev_b32_e32 v147, 1, v146
	v_lshl_add_u32 v155, v148, 11, v147
	v_lshl_add_u32 v188, v148, 6, s48
	global_load_dwordx4 v[200:203], v149, s[88:89]
	global_load_dwordx4 v[204:207], v149, s[88:89] offset:16
	global_load_dwordx4 v[208:211], v149, s[88:89] offset:512
	global_load_dwordx4 v[212:215], v149, s[88:89] offset:528
	v_add_u32_e32 v189, 0x10000, v149
	global_load_dwordx4 v[216:219], v189, s[88:89]
	global_load_dwordx4 v[220:223], v189, s[88:89] offset:16
	global_load_dwordx4 v[224:227], v189, s[88:89] offset:512
	global_load_dwordx4 v[228:231], v189, s[88:89] offset:528
	v_add_u32_e32 v189, 0x20000, v149
	global_load_dwordx4 v[232:235], v189, s[88:89]
	global_load_dwordx4 v[236:239], v189, s[88:89] offset:16
	global_load_dwordx4 v[240:243], v189, s[88:89] offset:512
	global_load_dwordx4 v[244:247], v189, s[88:89] offset:528
	v_add_u32_e32 v189, 0x30000, v149
	global_load_dwordx4 v[156:159], v189, s[88:89]
	global_load_dwordx4 v[160:163], v189, s[88:89] offset:16
	global_load_dwordx4 v[164:167], v189, s[88:89] offset:512
	global_load_dwordx4 v[168:171], v189, s[88:89] offset:528
	s_waitcnt vmcnt(12)
	v_pk_add_f32 v[200:201], v[126:127], v[200:201]
	v_pk_add_f32 v[202:203], v[128:129], v[202:203]
	v_pk_add_f32 v[204:205], v[122:123], v[204:205]
	v_pk_add_f32 v[206:207], v[124:125], v[206:207]
	v_pk_add_f32 v[208:209], v[118:119], v[208:209]
	v_pk_add_f32 v[210:211], v[120:121], v[210:211]
	v_pk_add_f32 v[212:213], v[114:115], v[212:213]
	v_pk_add_f32 v[214:215], v[116:117], v[214:215]
	v_cvt_pk_bf16_f32 v126, v200, v201
	v_cvt_pk_bf16_f32 v127, v202, v203
	v_cvt_pk_bf16_f32 v128, v204, v205
	v_cvt_pk_bf16_f32 v129, v206, v207
	v_cvt_pk_bf16_f32 v118, v208, v209
	v_cvt_pk_bf16_f32 v119, v210, v211
	v_cvt_pk_bf16_f32 v120, v212, v213
	v_cvt_pk_bf16_f32 v121, v214, v215
	v_mul_f32_e32 v173, v203, v203
	v_mul_f32_e32 v172, v201, v201
	v_mul_f32_e32 v174, v205, v205
	v_fmac_f32_e32 v172, v200, v200
	v_fmac_f32_e32 v173, v202, v202
	v_mul_f32_e32 v175, v207, v207
	v_fmac_f32_e32 v174, v204, v204
	v_add_f32_e32 v172, v172, v173
	v_fmac_f32_e32 v175, v206, v206
	v_add_f32_e32 v172, v172, v174
	v_add_f32_e32 v172, v175, v172
	v_mul_f32_e32 v177, v211, v211
	v_mul_f32_e32 v176, v209, v209
	v_mul_f32_e32 v178, v213, v213
	v_fmac_f32_e32 v176, v208, v208
	v_fmac_f32_e32 v177, v210, v210
	v_mul_f32_e32 v179, v215, v215
	v_fmac_f32_e32 v178, v212, v212
	v_add_f32_e32 v176, v176, v177
	v_fmac_f32_e32 v179, v214, v214
	v_add_f32_e32 v176, v176, v178
	v_add_f32_e32 v176, v179, v176
	v_add_f32_e32 v180, v172, v176
	v_mov_b32_e32 v191, v180
	s_nop 1
	v_permlane16_swap_b32_e32 v180, v191
	v_add_f32_e32 v180, v180, v191
	v_mov_b32_e32 v191, v180
	s_nop 1
	v_permlane32_swap_b32_e32 v180, v191
	v_add_f32_e32 v180, v180, v191
	v_add_u32_e32 v189, 0x80000, v149
	global_load_dwordx4 v[200:203], v189, s[88:89]
	global_load_dwordx4 v[204:207], v189, s[88:89] offset:16
	global_load_dwordx4 v[208:211], v189, s[88:89] offset:512
	global_load_dwordx4 v[212:215], v189, s[88:89] offset:528
	s_waitcnt vmcnt(12)
	v_pk_add_f32 v[216:217], v[110:111], v[216:217]
	v_pk_add_f32 v[218:219], v[112:113], v[218:219]
	v_pk_add_f32 v[220:221], v[106:107], v[220:221]
	v_pk_add_f32 v[222:223], v[108:109], v[222:223]
	v_pk_add_f32 v[224:225], v[102:103], v[224:225]
	v_pk_add_f32 v[226:227], v[104:105], v[226:227]
	v_pk_add_f32 v[228:229], v[98:99], v[228:229]
	v_pk_add_f32 v[230:231], v[100:101], v[230:231]
	v_cvt_pk_bf16_f32 v110, v216, v217
	v_cvt_pk_bf16_f32 v111, v218, v219
	v_cvt_pk_bf16_f32 v112, v220, v221
	v_cvt_pk_bf16_f32 v113, v222, v223
	v_cvt_pk_bf16_f32 v102, v224, v225
	v_cvt_pk_bf16_f32 v103, v226, v227
	v_cvt_pk_bf16_f32 v104, v228, v229
	v_cvt_pk_bf16_f32 v105, v230, v231
	v_mul_f32_e32 v173, v219, v219
	v_mul_f32_e32 v172, v217, v217
	v_mul_f32_e32 v174, v221, v221
	v_fmac_f32_e32 v172, v216, v216
	v_fmac_f32_e32 v173, v218, v218
	v_mul_f32_e32 v175, v223, v223
	v_fmac_f32_e32 v174, v220, v220
	v_add_f32_e32 v172, v172, v173
	v_fmac_f32_e32 v175, v222, v222
	v_add_f32_e32 v172, v172, v174
	v_add_f32_e32 v172, v175, v172
	v_mul_f32_e32 v177, v227, v227
	v_mul_f32_e32 v176, v225, v225
	v_mul_f32_e32 v178, v229, v229
	v_fmac_f32_e32 v176, v224, v224
	v_fmac_f32_e32 v177, v226, v226
	v_mul_f32_e32 v179, v231, v231
	v_fmac_f32_e32 v178, v228, v228
	v_add_f32_e32 v176, v176, v177
	v_fmac_f32_e32 v179, v230, v230
	v_add_f32_e32 v176, v176, v178
	v_add_f32_e32 v176, v179, v176
	v_add_f32_e32 v181, v172, v176
	v_mov_b32_e32 v191, v181
	s_nop 1
	v_permlane16_swap_b32_e32 v181, v191
	v_add_f32_e32 v181, v181, v191
	v_mov_b32_e32 v191, v181
	s_nop 1
	v_permlane32_swap_b32_e32 v181, v191
	v_add_f32_e32 v181, v181, v191
	v_add_u32_e32 v189, 0x90000, v149
	global_load_dwordx4 v[216:219], v189, s[88:89]
	global_load_dwordx4 v[220:223], v189, s[88:89] offset:16
	global_load_dwordx4 v[224:227], v189, s[88:89] offset:512
	global_load_dwordx4 v[228:231], v189, s[88:89] offset:528
	s_waitcnt vmcnt(12)
; DI unsigned pk2(float lo, float hi) { const f32x2 v = {lo, hi}; const bf16x2_t b = __builtin_convertvector(v, bf16x2_t); return __builtin_bit_cast(unsigned, b); }
;     DI void operator()(const Acc& acc, const Unit& u, int wr, int wc, int fr, int fq) const {
;     ...
;                 const int r = row0 + ai * 128 + m * 16; float ss = 0.f;
; #pragma unroll
;                 for (int bj = 0; bj < 2; ++bj) {
;                     const int c0 = u.pn * 256 + bj * 128 + wc * 32 + 8 * fq; const size_t off = (size_t)r * DM + c0;
;                     f32x4 b0, b1;
;                     if (MODE == 1) { b0 = *(const f32x4*)(base + off); b1 = *(const f32x4*)(base + off + 4); }
;                     else { const u32x4 w = *(const u32x4*)(baseb + off); b0 = (f32x4){bflo(w.x), bfhi(w.x), bflo(w.y), bfhi(w.y)}; b1 = (f32x4){bflo(w.z), bfhi(w.z), bflo(w.w), bfhi(w.w)}; }
;                     const f32x4 h0 = b0 + acc[ai][bj][m][0], h1 = b1 + acc[ai][bj][m][1];
;                     ss += (h0[0] * h0[0] + h0[1] * h0[1]) + (h0[2] * h0[2] + h0[3] * h0[3]) + (h1[0] * h1[0] + h1[1] * h1[1]) + (h1[2] * h1[2] + h1[3] * h1[3]);
;                     if (MODE == 1) { u32x4 w; w.x = pk2(h0[0], h0[1]); w.y = pk2(h0[2], h0[3]); w.z = pk2(h1[0], h1[1]); w.w = pk2(h1[2], h1[3]); *(u32x4*)(HB + off) = w; }
;                     else { u32x4 w; w.x = pk2(h0[0], h0[1]); w.y = pk2(h0[2], h0[3]); w.z = pk2(h1[0], h1[1]); w.w = pk2(h1[2], h1[3]); *(u32x4*)(HB + off) = w; }
;                 }
;                 ss += __shfl_xor(ss, 16); ss += __shfl_xor(ss, 32);
;                 if (fq == 0) SS[(size_t)r * 16 + u.pn * 4 + wc] = ss;
	v_pk_add_f32 v[232:233], v[94:95], v[232:233]
	v_pk_add_f32 v[234:235], v[96:97], v[234:235]
	v_pk_add_f32 v[236:237], v[90:91], v[236:237]
	v_pk_add_f32 v[238:239], v[92:93], v[238:239]
	v_pk_add_f32 v[240:241], v[86:87], v[240:241]
	v_pk_add_f32 v[242:243], v[88:89], v[242:243]
	v_pk_add_f32 v[244:245], v[82:83], v[244:245]
	v_pk_add_f32 v[246:247], v[84:85], v[246:247]
	v_cvt_pk_bf16_f32 v94, v232, v233
	v_cvt_pk_bf16_f32 v95, v234, v235
	v_cvt_pk_bf16_f32 v96, v236, v237
	v_cvt_pk_bf16_f32 v97, v238, v239
	v_cvt_pk_bf16_f32 v86, v240, v241
	v_cvt_pk_bf16_f32 v87, v242, v243
	v_cvt_pk_bf16_f32 v88, v244, v245
	v_cvt_pk_bf16_f32 v89, v246, v247
	v_mul_f32_e32 v173, v235, v235
	v_mul_f32_e32 v172, v233, v233
	v_mul_f32_e32 v174, v237, v237
	v_fmac_f32_e32 v172, v232, v232
	v_fmac_f32_e32 v173, v234, v234
	v_mul_f32_e32 v175, v239, v239
	v_fmac_f32_e32 v174, v236, v236
	v_add_f32_e32 v172, v172, v173
	v_fmac_f32_e32 v175, v238, v238
	v_add_f32_e32 v172, v172, v174
	v_add_f32_e32 v172, v175, v172
	v_mul_f32_e32 v177, v243, v243
	v_mul_f32_e32 v176, v241, v241
	v_mul_f32_e32 v178, v245, v245
	v_fmac_f32_e32 v176, v240, v240
	v_fmac_f32_e32 v177, v242, v242
	v_mul_f32_e32 v179, v247, v247
	v_fmac_f32_e32 v178, v244, v244
	v_add_f32_e32 v176, v176, v177
	v_fmac_f32_e32 v179, v246, v246
	v_add_f32_e32 v176, v176, v178
	v_add_f32_e32 v176, v179, v176
	v_add_f32_e32 v182, v172, v176
	v_mov_b32_e32 v191, v182
	s_nop 1
	v_permlane16_swap_b32_e32 v182, v191
	v_add_f32_e32 v182, v182, v191
	v_mov_b32_e32 v191, v182
	s_nop 1
	v_permlane32_swap_b32_e32 v182, v191
	v_add_f32_e32 v182, v182, v191
	v_add_u32_e32 v189, 0xa0000, v149
	global_load_dwordx4 v[232:235], v189, s[88:89]
	global_load_dwordx4 v[236:239], v189, s[88:89] offset:16
	global_load_dwordx4 v[240:243], v189, s[88:89] offset:512
	global_load_dwordx4 v[244:247], v189, s[88:89] offset:528
	s_waitcnt vmcnt(12)
	v_pk_add_f32 v[156:157], v[78:79], v[156:157]
	v_pk_add_f32 v[158:159], v[80:81], v[158:159]
	v_pk_add_f32 v[160:161], v[74:75], v[160:161]
	v_pk_add_f32 v[162:163], v[76:77], v[162:163]
	v_pk_add_f32 v[164:165], v[70:71], v[164:165]
	v_pk_add_f32 v[166:167], v[72:73], v[166:167]
	v_pk_add_f32 v[168:169], v[66:67], v[168:169]
	v_pk_add_f32 v[170:171], v[68:69], v[170:171]
	v_cvt_pk_bf16_f32 v78, v156, v157
	v_cvt_pk_bf16_f32 v79, v158, v159
	v_cvt_pk_bf16_f32 v80, v160, v161
	v_cvt_pk_bf16_f32 v81, v162, v163
	v_cvt_pk_bf16_f32 v70, v164, v165
	v_cvt_pk_bf16_f32 v71, v166, v167
	v_cvt_pk_bf16_f32 v72, v168, v169
	v_cvt_pk_bf16_f32 v73, v170, v171
	v_mul_f32_e32 v173, v159, v159
	v_mul_f32_e32 v172, v157, v157
	v_mul_f32_e32 v174, v161, v161
	v_fmac_f32_e32 v172, v156, v156
	v_fmac_f32_e32 v173, v158, v158
	v_mul_f32_e32 v175, v163, v163
	v_fmac_f32_e32 v174, v160, v160
	v_add_f32_e32 v172, v172, v173
	v_fmac_f32_e32 v175, v162, v162
	v_add_f32_e32 v172, v172, v174
	v_add_f32_e32 v172, v175, v172
	v_mul_f32_e32 v177, v167, v167
	v_mul_f32_e32 v176, v165, v165
	v_mul_f32_e32 v178, v169, v169
	v_fmac_f32_e32 v176, v164, v164
	v_fmac_f32_e32 v177, v166, v166
	v_mul_f32_e32 v179, v171, v171
	v_fmac_f32_e32 v178, v168, v168
	v_add_f32_e32 v176, v176, v177
	v_fmac_f32_e32 v179, v170, v170
	v_add_f32_e32 v176, v176, v178
	v_add_f32_e32 v176, v179, v176
	v_add_f32_e32 v183, v172, v176
	v_mov_b32_e32 v191, v183
	s_nop 1
	v_permlane16_swap_b32_e32 v183, v191
	v_add_f32_e32 v183, v183, v191
	v_mov_b32_e32 v191, v183
	s_nop 1
	v_permlane32_swap_b32_e32 v183, v191
	v_add_f32_e32 v183, v183, v191
	v_add_u32_e32 v189, 0xb0000, v149
	global_load_dwordx4 v[156:159], v189, s[88:89]
	global_load_dwordx4 v[160:163], v189, s[88:89] offset:16
	global_load_dwordx4 v[164:167], v189, s[88:89] offset:512
	global_load_dwordx4 v[168:171], v189, s[88:89] offset:528
	global_store_dwordx4 v155, v[126:129], s[12:13]
	global_store_dwordx4 v155, v[118:121], s[12:13] offset:256
	v_add_u32_e32 v190, 0x8000, v155
	global_store_dwordx4 v190, v[110:113], s[12:13]
	global_store_dwordx4 v190, v[102:105], s[12:13] offset:256
	v_add_u32_e32 v190, 0x10000, v155
	global_store_dwordx4 v190, v[94:97], s[12:13]
	global_store_dwordx4 v190, v[86:89], s[12:13] offset:256
	v_add_u32_e32 v190, 0x18000, v155
	global_store_dwordx4 v190, v[78:81], s[12:13]
	global_store_dwordx4 v190, v[70:73], s[12:13] offset:256
	s_waitcnt vmcnt(20)
	v_pk_add_f32 v[200:201], v[62:63], v[200:201]
	v_pk_add_f32 v[202:203], v[64:65], v[202:203]
	v_pk_add_f32 v[204:205], v[58:59], v[204:205]
	v_pk_add_f32 v[206:207], v[60:61], v[206:207]
	v_pk_add_f32 v[208:209], v[54:55], v[208:209]
	v_pk_add_f32 v[210:211], v[56:57], v[210:211]
	v_pk_add_f32 v[212:213], v[50:51], v[212:213]
	v_pk_add_f32 v[214:215], v[52:53], v[214:215]
	v_cvt_pk_bf16_f32 v62, v200, v201
	v_cvt_pk_bf16_f32 v63, v202, v203
	v_cvt_pk_bf16_f32 v64, v204, v205
	v_cvt_pk_bf16_f32 v65, v206, v207
	v_cvt_pk_bf16_f32 v54, v208, v209
	v_cvt_pk_bf16_f32 v55, v210, v211
	v_cvt_pk_bf16_f32 v56, v212, v213
	v_cvt_pk_bf16_f32 v57, v214, v215
	v_mul_f32_e32 v173, v203, v203
	v_mul_f32_e32 v172, v201, v201
	v_mul_f32_e32 v174, v205, v205
	v_fmac_f32_e32 v172, v200, v200
	v_fmac_f32_e32 v173, v202, v202
	v_mul_f32_e32 v175, v207, v207
	v_fmac_f32_e32 v174, v204, v204
	v_add_f32_e32 v172, v172, v173
	v_fmac_f32_e32 v175, v206, v206
	v_add_f32_e32 v172, v172, v174
	v_add_f32_e32 v172, v175, v172
	v_mul_f32_e32 v177, v211, v211
	v_mul_f32_e32 v176, v209, v209
	v_mul_f32_e32 v178, v213, v213
	v_fmac_f32_e32 v176, v208, v208
	v_fmac_f32_e32 v177, v210, v210
	v_mul_f32_e32 v179, v215, v215
	v_fmac_f32_e32 v178, v212, v212
	v_add_f32_e32 v176, v176, v177
	v_fmac_f32_e32 v179, v214, v214
	v_add_f32_e32 v176, v176, v178
	v_add_f32_e32 v176, v179, v176
	v_add_f32_e32 v184, v172, v176
	v_mov_b32_e32 v191, v184
	s_nop 1
	v_permlane16_swap_b32_e32 v184, v191
	v_add_f32_e32 v184, v184, v191
	v_mov_b32_e32 v191, v184
	s_nop 1
	v_permlane32_swap_b32_e32 v184, v191
	v_add_f32_e32 v184, v184, v191
	v_add_u32_e32 v190, 0x40000, v155
	global_store_dwordx4 v190, v[62:65], s[12:13]
	global_store_dwordx4 v190, v[54:57], s[12:13] offset:256
	s_waitcnt vmcnt(18)
; DI unsigned pk2(float lo, float hi) { const f32x2 v = {lo, hi}; const bf16x2_t b = __builtin_convertvector(v, bf16x2_t); return __builtin_bit_cast(unsigned, b); }
;     DI void operator()(const Acc& acc, const Unit& u, int wr, int wc, int fr, int fq) const {
;     ...
;                 const int r = row0 + ai * 128 + m * 16; float ss = 0.f;
; #pragma unroll
;                 for (int bj = 0; bj < 2; ++bj) {
;                     const int c0 = u.pn * 256 + bj * 128 + wc * 32 + 8 * fq; const size_t off = (size_t)r * DM + c0;
;                     f32x4 b0, b1;
;                     if (MODE == 1) { b0 = *(const f32x4*)(base + off); b1 = *(const f32x4*)(base + off + 4); }
;                     else { const u32x4 w = *(const u32x4*)(baseb + off); b0 = (f32x4){bflo(w.x), bfhi(w.x), bflo(w.y), bfhi(w.y)}; b1 = (f32x4){bflo(w.z), bfhi(w.z), bflo(w.w), bfhi(w.w)}; }
;                     const f32x4 h0 = b0 + acc[ai][bj][m][0], h1 = b1 + acc[ai][bj][m][1];
;                     ss += (h0[0] * h0[0] + h0[1] * h0[1]) + (h0[2] * h0[2] + h0[3] * h0[3]) + (h1[0] * h1[0] + h1[1] * h1[1]) + (h1[2] * h1[2] + h1[3] * h1[3]);
;                     if (MODE == 1) { u32x4 w; w.x = pk2(h0[0], h0[1]); w.y = pk2(h0[2], h0[3]); w.z = pk2(h1[0], h1[1]); w.w = pk2(h1[2], h1[3]); *(u32x4*)(HB + off) = w; }
;                     else { u32x4 w; w.x = pk2(h0[0], h0[1]); w.y = pk2(h0[2], h0[3]); w.z = pk2(h1[0], h1[1]); w.w = pk2(h1[2], h1[3]); *(u32x4*)(HB + off) = w; }
;                 }
;                 ss += __shfl_xor(ss, 16); ss += __shfl_xor(ss, 32);
;                 if (fq == 0) SS[(size_t)r * 16 + u.pn * 4 + wc] = ss;
	v_pk_add_f32 v[216:217], v[46:47], v[216:217]
	v_pk_add_f32 v[218:219], v[48:49], v[218:219]
	v_pk_add_f32 v[220:221], v[42:43], v[220:221]
	v_pk_add_f32 v[222:223], v[44:45], v[222:223]
	v_pk_add_f32 v[224:225], v[38:39], v[224:225]
	v_pk_add_f32 v[226:227], v[40:41], v[226:227]
	v_pk_add_f32 v[228:229], v[34:35], v[228:229]
	v_pk_add_f32 v[230:231], v[36:37], v[230:231]
	v_cvt_pk_bf16_f32 v46, v216, v217
	v_cvt_pk_bf16_f32 v47, v218, v219
	v_cvt_pk_bf16_f32 v48, v220, v221
	v_cvt_pk_bf16_f32 v49, v222, v223
	v_cvt_pk_bf16_f32 v38, v224, v225
	v_cvt_pk_bf16_f32 v39, v226, v227
	v_cvt_pk_bf16_f32 v40, v228, v229
	v_cvt_pk_bf16_f32 v41, v230, v231
	v_mul_f32_e32 v173, v219, v219
	v_mul_f32_e32 v172, v217, v217
	v_mul_f32_e32 v174, v221, v221
	v_fmac_f32_e32 v172, v216, v216
	v_fmac_f32_e32 v173, v218, v218
	v_mul_f32_e32 v175, v223, v223
	v_fmac_f32_e32 v174, v220, v220
	v_add_f32_e32 v172, v172, v173
	v_fmac_f32_e32 v175, v222, v222
	v_add_f32_e32 v172, v172, v174
	v_add_f32_e32 v172, v175, v172
	v_mul_f32_e32 v177, v227, v227
	v_mul_f32_e32 v176, v225, v225
	v_mul_f32_e32 v178, v229, v229
	v_fmac_f32_e32 v176, v224, v224
	v_fmac_f32_e32 v177, v226, v226
	v_mul_f32_e32 v179, v231, v231
	v_fmac_f32_e32 v178, v228, v228
	v_add_f32_e32 v176, v176, v177
	v_fmac_f32_e32 v179, v230, v230
	v_add_f32_e32 v176, v176, v178
	v_add_f32_e32 v176, v179, v176
	v_add_f32_e32 v185, v172, v176
	v_mov_b32_e32 v191, v185
	s_nop 1
	v_permlane16_swap_b32_e32 v185, v191
	v_add_f32_e32 v185, v185, v191
	v_mov_b32_e32 v191, v185
	s_nop 1
	v_permlane32_swap_b32_e32 v185, v191
	v_add_f32_e32 v185, v185, v191
	v_add_u32_e32 v190, 0x48000, v155
	global_store_dwordx4 v190, v[46:49], s[12:13]
	global_store_dwordx4 v190, v[38:41], s[12:13] offset:256
	s_waitcnt vmcnt(16)
	v_pk_add_f32 v[232:233], v[30:31], v[232:233]
	v_pk_add_f32 v[234:235], v[32:33], v[234:235]
	v_pk_add_f32 v[236:237], v[26:27], v[236:237]
	v_pk_add_f32 v[238:239], v[28:29], v[238:239]
	v_pk_add_f32 v[240:241], v[22:23], v[240:241]
	v_pk_add_f32 v[242:243], v[24:25], v[242:243]
	v_pk_add_f32 v[244:245], v[18:19], v[244:245]
	v_pk_add_f32 v[246:247], v[20:21], v[246:247]
	v_cvt_pk_bf16_f32 v30, v232, v233
	v_cvt_pk_bf16_f32 v31, v234, v235
	v_cvt_pk_bf16_f32 v32, v236, v237
	v_cvt_pk_bf16_f32 v33, v238, v239
	v_cvt_pk_bf16_f32 v22, v240, v241
	v_cvt_pk_bf16_f32 v23, v242, v243
	v_cvt_pk_bf16_f32 v24, v244, v245
	v_cvt_pk_bf16_f32 v25, v246, v247
	v_mul_f32_e32 v173, v235, v235
	v_mul_f32_e32 v172, v233, v233
	v_mul_f32_e32 v174, v237, v237
	v_fmac_f32_e32 v172, v232, v232
	v_fmac_f32_e32 v173, v234, v234
	v_mul_f32_e32 v175, v239, v239
	v_fmac_f32_e32 v174, v236, v236
	v_add_f32_e32 v172, v172, v173
	v_fmac_f32_e32 v175, v238, v238
	v_add_f32_e32 v172, v172, v174
	v_add_f32_e32 v172, v175, v172
	v_mul_f32_e32 v177, v243, v243
	v_mul_f32_e32 v176, v241, v241
	v_mul_f32_e32 v178, v245, v245
	v_fmac_f32_e32 v176, v240, v240
	v_fmac_f32_e32 v177, v242, v242
	v_mul_f32_e32 v179, v247, v247
	v_fmac_f32_e32 v178, v244, v244
	v_add_f32_e32 v176, v176, v177
	v_fmac_f32_e32 v179, v246, v246
	v_add_f32_e32 v176, v176, v178
	v_add_f32_e32 v176, v179, v176
	v_add_f32_e32 v186, v172, v176
	v_mov_b32_e32 v191, v186
	s_nop 1
	v_permlane16_swap_b32_e32 v186, v191
	v_add_f32_e32 v186, v186, v191
	v_mov_b32_e32 v191, v186
	s_nop 1
	v_permlane32_swap_b32_e32 v186, v191
	v_add_f32_e32 v186, v186, v191
	v_add_u32_e32 v190, 0x50000, v155
	global_store_dwordx4 v190, v[30:33], s[12:13]
	global_store_dwordx4 v190, v[22:25], s[12:13] offset:256
	s_waitcnt vmcnt(14)
	v_pk_add_f32 v[156:157], v[14:15], v[156:157]
	v_pk_add_f32 v[158:159], v[16:17], v[158:159]
	v_pk_add_f32 v[160:161], v[10:11], v[160:161]
	v_pk_add_f32 v[162:163], v[12:13], v[162:163]
	v_pk_add_f32 v[164:165], v[6:7], v[164:165]
	v_pk_add_f32 v[166:167], v[8:9], v[166:167]
	v_pk_add_f32 v[168:169], v[2:3], v[168:169]
	v_pk_add_f32 v[170:171], v[4:5], v[170:171]
	v_cvt_pk_bf16_f32 v14, v156, v157
	v_cvt_pk_bf16_f32 v15, v158, v159
	v_cvt_pk_bf16_f32 v16, v160, v161
	v_cvt_pk_bf16_f32 v17, v162, v163
	v_cvt_pk_bf16_f32 v6, v164, v165
	v_cvt_pk_bf16_f32 v7, v166, v167
	v_cvt_pk_bf16_f32 v8, v168, v169
	v_cvt_pk_bf16_f32 v9, v170, v171
	v_mul_f32_e32 v173, v159, v159
	v_mul_f32_e32 v172, v157, v157
	v_mul_f32_e32 v174, v161, v161
	v_fmac_f32_e32 v172, v156, v156
	v_fmac_f32_e32 v173, v158, v158
	v_mul_f32_e32 v175, v163, v163
	v_fmac_f32_e32 v174, v160, v160
	v_add_f32_e32 v172, v172, v173
	v_fmac_f32_e32 v175, v162, v162
	v_add_f32_e32 v172, v172, v174
	v_add_f32_e32 v172, v175, v172
	v_mul_f32_e32 v177, v167, v167
	v_mul_f32_e32 v176, v165, v165
	v_mul_f32_e32 v178, v169, v169
	v_fmac_f32_e32 v176, v164, v164
	v_fmac_f32_e32 v177, v166, v166
	v_mul_f32_e32 v179, v171, v171
	v_fmac_f32_e32 v178, v168, v168
	v_add_f32_e32 v176, v176, v177
	v_fmac_f32_e32 v179, v170, v170
	v_add_f32_e32 v176, v176, v178
	v_add_f32_e32 v176, v179, v176
	v_add_f32_e32 v187, v172, v176
	v_mov_b32_e32 v191, v187
	s_nop 1
	v_permlane16_swap_b32_e32 v187, v191
	v_add_f32_e32 v187, v187, v191
	v_mov_b32_e32 v191, v187
	s_nop 1
	v_permlane32_swap_b32_e32 v187, v191
	v_add_f32_e32 v187, v187, v191
	v_add_u32_e32 v190, 0x58000, v155
	global_store_dwordx4 v190, v[14:17], s[12:13]
	global_store_dwordx4 v190, v[6:9], s[12:13] offset:256
	s_and_saveexec_b64 s[50:51], s[4:5]
	global_store_dword v188, v180, s[14:15]
	v_add_u32_e32 v189, 0x400, v188
	global_store_dword v189, v181, s[14:15]
	v_add_u32_e32 v189, 0x800, v188
	global_store_dword v189, v182, s[14:15]
	v_add_u32_e32 v189, 0xc00, v188
	global_store_dword v189, v183, s[14:15]
	v_add_u32_e32 v189, 0x2000, v188
	global_store_dword v189, v184, s[14:15]
	v_add_u32_e32 v189, 0x2400, v188
	global_store_dword v189, v185, s[14:15]
	v_add_u32_e32 v189, 0x2800, v188
	global_store_dword v189, v186, s[14:15]
	v_add_u32_e32 v189, 0x2c00, v188
	global_store_dword v189, v187, s[14:15]
